# attention output scaling: 4 v_mul_f32 per 8-byte group -> 2 in-place v_pk_mul_f32 (rden broadcast)
# baseline (speedup 1.0000x reference)
.LBB0_347:
	v_cndmask_b32_e64 v72, v48, v212, s[2:3]
	v_cndmask_b32_e64 v167, v72, v48, s[4:5]
	v_max3_f32 v48, v98, s64, v105
	v_max3_f32 v48, v48, v104, v103
	v_max3_f32 v48, v48, v102, v101
	v_max3_f32 v48, v48, v100, v99
	v_max3_f32 v48, v48, v71, v70
	v_max3_f32 v48, v48, v69, v68
	v_max3_f32 v48, v48, v67, v66
	v_max3_f32 v48, v48, v65, v64
	v_max3_f32 v48, v48, v32, v33
	v_max3_f32 v48, v48, v34, v35
	v_max3_f32 v48, v48, v36, v37
	v_max3_f32 v48, v48, v38, v39
	v_max3_f32 v48, v48, v40, v41
	v_max3_f32 v48, v48, v42, v43
	v_max3_f32 v48, v48, v44, v45
	v_max3_f32 v48, v48, v46, v47
	v_max3_f32 v48, v48, v16, v17
	v_max3_f32 v48, v48, v18, v19
	v_max3_f32 v48, v48, v20, v21
	v_max3_f32 v48, v48, v22, v23
	v_max3_f32 v48, v48, v24, v25
	v_max3_f32 v48, v48, v26, v27
	v_max3_f32 v48, v48, v28, v29
	v_max3_f32 v48, v48, v30, v31
	v_max3_f32 v48, v48, v0, v1
	v_max3_f32 v48, v48, v2, v3
	v_max3_f32 v48, v48, v4, v5
	v_max3_f32 v48, v48, v6, v7
	v_max3_f32 v48, v48, v8, v9
	v_max3_f32 v48, v48, v10, v11
	v_max3_f32 v48, v48, v12, v13
	v_cndmask_b32_e64 v166, v212, v49, s[4:5]
	v_max3_f32 v48, v48, v14, v15
	v_cndmask_b32_e64 v168, v50, v212, s[6:7]
	v_cndmask_b32_e64 v169, v51, v212, s[8:9]
	v_max3_f32 v48, v48, v167, v166
	v_cndmask_b32_e64 v170, v52, v212, s[10:11]
	v_cndmask_b32_e64 v171, v53, v212, s[12:13]
	v_max3_f32 v48, v48, v168, v169
	v_cndmask_b32_e64 v172, v54, v212, s[14:15]
	v_cndmask_b32_e64 v173, v55, v212, s[16:17]
	v_max3_f32 v48, v48, v170, v171
	v_cndmask_b32_e64 v174, v56, v212, s[18:19]
	v_cndmask_b32_e64 v175, v57, v212, s[20:21]
	v_max3_f32 v48, v48, v172, v173
	v_cndmask_b32_e64 v176, v58, v212, s[22:23]
	v_cndmask_b32_e64 v177, v59, v212, s[24:25]
	v_max3_f32 v48, v48, v174, v175
	v_cndmask_b32_e64 v178, v60, v212, s[26:27]
	v_cndmask_b32_e64 v179, v61, v212, s[28:29]
	v_max3_f32 v48, v48, v176, v177
	v_cndmask_b32_e64 v180, v62, v212, s[30:31]
	v_cndmask_b32_e64 v181, v63, v212, s[34:35]
	v_max3_f32 v48, v48, v178, v179
	v_max3_f32 v48, v48, v180, v181
	ds_bpermute_b32 v49, v188, v48
	v_or_b32_e32 v153, s89, v118
	v_readlane_b32 s0, v255, 16
	s_add_i32 s96, s96, s1
	s_add_i32 s90, s90, s0
	s_waitcnt lgkmcnt(0)
	v_max3_f32 v213, v48, v49, v96
	v_sub_f32_e32 v50, v104, v213
	v_exp_f32_e32 v154, v50
	v_sub_f32_e32 v50, v103, v213
	v_exp_f32_e32 v155, v50
	v_sub_f32_e32 v50, v102, v213
	v_exp_f32_e32 v160, v50
	v_sub_f32_e32 v50, v101, v213
	v_exp_f32_e32 v161, v50
	v_sub_f32_e32 v50, v100, v213
	v_sub_f32_e32 v48, v98, v213
	v_exp_f32_e32 v164, v50
	v_sub_f32_e32 v50, v99, v213
	v_exp_f32_e32 v110, v48
	v_sub_f32_e32 v48, v105, v213
	v_exp_f32_e32 v165, v50
	v_sub_f32_e32 v50, v71, v213
	v_exp_f32_e32 v111, v48
	v_exp_f32_e32 v102, v50
	v_sub_f32_e32 v50, v70, v213
	v_exp_f32_e32 v103, v50
	v_pk_add_f32 v[232:233], v[68:69], v[212:213] op_sel:[0,1] op_sel_hi:[1,1] neg_lo:[0,1] neg_hi:[0,1]
	v_pk_add_f32 v[234:235], v[34:35], v[212:213] op_sel:[0,1] op_sel_hi:[1,1] neg_lo:[0,1] neg_hi:[0,1]
	v_exp_f32_e32 v112, v233
	v_exp_f32_e32 v106, v234
	v_exp_f32_e32 v113, v232
	v_pk_add_f32 v[232:233], v[66:67], v[212:213] op_sel:[0,1] op_sel_hi:[1,1] neg_lo:[0,1] neg_hi:[0,1]
	v_exp_f32_e32 v107, v235
	v_pk_add_f32 v[234:235], v[36:37], v[212:213] op_sel:[0,1] op_sel_hi:[1,1] neg_lo:[0,1] neg_hi:[0,1]
	v_pk_add_f32 v[48:49], v[110:111], 0 op_sel_hi:[1,0]
	v_exp_f32_e32 v156, v233
	v_exp_f32_e32 v118, v234
	v_pk_add_f32 v[48:49], v[154:155], v[48:49]
	v_exp_f32_e32 v157, v232
	v_pk_add_f32 v[232:233], v[64:65], v[212:213] op_sel:[0,1] op_sel_hi:[1,1] neg_lo:[0,1] neg_hi:[0,1]
	v_exp_f32_e32 v119, v235
	v_pk_add_f32 v[234:235], v[38:39], v[212:213] op_sel:[0,1] op_sel_hi:[1,1] neg_lo:[0,1] neg_hi:[0,1]
	v_pk_add_f32 v[48:49], v[160:161], v[48:49]
	v_exp_f32_e32 v162, v233
	v_pk_add_f32 v[236:237], v[32:33], v[212:213] op_sel:[0,1] op_sel_hi:[1,1] neg_lo:[0,1] neg_hi:[0,1]
	v_exp_f32_e32 v158, v234
	v_pk_add_f32 v[48:49], v[164:165], v[48:49]
	v_exp_f32_e32 v163, v232
	v_exp_f32_e32 v78, v236
	v_exp_f32_e32 v159, v235
	v_pk_add_f32 v[232:233], v[40:41], v[212:213] op_sel:[0,1] op_sel_hi:[1,1] neg_lo:[0,1] neg_hi:[0,1]
	v_pk_add_f32 v[48:49], v[102:103], v[48:49]
	v_exp_f32_e32 v79, v237
	v_exp_f32_e32 v68, v232
	v_pk_add_f32 v[48:49], v[112:113], v[48:49]
	v_exp_f32_e32 v69, v233
	v_pk_add_f32 v[232:233], v[42:43], v[212:213] op_sel:[0,1] op_sel_hi:[1,1] neg_lo:[0,1] neg_hi:[0,1]
	v_pk_add_f32 v[234:235], v[18:19], v[212:213] op_sel:[0,1] op_sel_hi:[1,1] neg_lo:[0,1] neg_hi:[0,1]
	v_pk_add_f32 v[236:237], v[2:3], v[212:213] op_sel:[0,1] op_sel_hi:[1,1] neg_lo:[0,1] neg_hi:[0,1]
	v_pk_add_f32 v[48:49], v[156:157], v[48:49]
	v_exp_f32_e32 v76, v232
	v_exp_f32_e32 v72, v234
	v_exp_f32_e32 v60, v236
	v_pk_add_f32 v[48:49], v[162:163], v[48:49]
	v_exp_f32_e32 v77, v233
	v_pk_add_f32 v[232:233], v[44:45], v[212:213] op_sel:[0,1] op_sel_hi:[1,1] neg_lo:[0,1] neg_hi:[0,1]
	v_exp_f32_e32 v73, v235
	v_pk_add_f32 v[234:235], v[20:21], v[212:213] op_sel:[0,1] op_sel_hi:[1,1] neg_lo:[0,1] neg_hi:[0,1]
	v_exp_f32_e32 v61, v237
	v_pk_add_f32 v[236:237], v[4:5], v[212:213] op_sel:[0,1] op_sel_hi:[1,1] neg_lo:[0,1] neg_hi:[0,1]
	v_pk_add_f32 v[32:33], v[78:79], v[48:49]
	v_exp_f32_e32 v104, v232
	v_exp_f32_e32 v100, v234
	v_exp_f32_e32 v66, v236
	v_pk_add_f32 v[32:33], v[106:107], v[32:33]
	v_exp_f32_e32 v105, v233
	v_pk_add_f32 v[232:233], v[46:47], v[212:213] op_sel:[0,1] op_sel_hi:[1,1] neg_lo:[0,1] neg_hi:[0,1]
	v_exp_f32_e32 v101, v235
	v_pk_add_f32 v[234:235], v[22:23], v[212:213] op_sel:[0,1] op_sel_hi:[1,1] neg_lo:[0,1] neg_hi:[0,1]
	v_exp_f32_e32 v67, v237
	v_pk_add_f32 v[236:237], v[6:7], v[212:213] op_sel:[0,1] op_sel_hi:[1,1] neg_lo:[0,1] neg_hi:[0,1]
	v_pk_add_f32 v[32:33], v[118:119], v[32:33]
	v_exp_f32_e32 v114, v232
	v_pk_add_f32 v[238:239], v[16:17], v[212:213] op_sel:[0,1] op_sel_hi:[1,1] neg_lo:[0,1] neg_hi:[0,1]
	v_exp_f32_e32 v108, v234
	v_exp_f32_e32 v74, v236
	v_pk_add_f32 v[32:33], v[158:159], v[32:33]
	v_exp_f32_e32 v115, v233
	v_exp_f32_e32 v64, v238
	v_exp_f32_e32 v109, v235
	v_pk_add_f32 v[232:233], v[24:25], v[212:213] op_sel:[0,1] op_sel_hi:[1,1] neg_lo:[0,1] neg_hi:[0,1]
	v_exp_f32_e32 v75, v237
	v_pk_add_f32 v[234:235], v[8:9], v[212:213] op_sel:[0,1] op_sel_hi:[1,1] neg_lo:[0,1] neg_hi:[0,1]
	v_pk_add_f32 v[32:33], v[68:69], v[32:33]
	v_exp_f32_e32 v65, v239
	v_exp_f32_e32 v58, v232
	v_exp_f32_e32 v48, v234
	v_pk_add_f32 v[32:33], v[76:77], v[32:33]
	v_exp_f32_e32 v59, v233
	v_pk_add_f32 v[232:233], v[26:27], v[212:213] op_sel:[0,1] op_sel_hi:[1,1] neg_lo:[0,1] neg_hi:[0,1]
	v_exp_f32_e32 v49, v235
	v_pk_add_f32 v[234:235], v[10:11], v[212:213] op_sel:[0,1] op_sel_hi:[1,1] neg_lo:[0,1] neg_hi:[0,1]
	v_pk_add_f32 v[32:33], v[104:105], v[32:33]
	v_exp_f32_e32 v62, v232
	v_exp_f32_e32 v50, v234
	v_pk_add_f32 v[32:33], v[114:115], v[32:33]
	v_exp_f32_e32 v63, v233
	v_pk_add_f32 v[232:233], v[28:29], v[212:213] op_sel:[0,1] op_sel_hi:[1,1] neg_lo:[0,1] neg_hi:[0,1]
	v_exp_f32_e32 v51, v235
	v_pk_add_f32 v[234:235], v[12:13], v[212:213] op_sel:[0,1] op_sel_hi:[1,1] neg_lo:[0,1] neg_hi:[0,1]
	v_pk_add_f32 v[16:17], v[64:65], v[32:33]
	v_exp_f32_e32 v70, v232
	v_exp_f32_e32 v52, v234
	v_pk_add_f32 v[16:17], v[72:73], v[16:17]
	v_exp_f32_e32 v71, v233
	v_pk_add_f32 v[232:233], v[30:31], v[212:213] op_sel:[0,1] op_sel_hi:[1,1] neg_lo:[0,1] neg_hi:[0,1]
	v_exp_f32_e32 v53, v235
	v_pk_add_f32 v[234:235], v[14:15], v[212:213] op_sel:[0,1] op_sel_hi:[1,1] neg_lo:[0,1] neg_hi:[0,1]
	v_pk_add_f32 v[16:17], v[100:101], v[16:17]
	v_exp_f32_e32 v98, v232
	v_pk_add_f32 v[236:237], v[0:1], v[212:213] op_sel:[0,1] op_sel_hi:[1,1] neg_lo:[0,1] neg_hi:[0,1]
	v_exp_f32_e32 v54, v234
	v_pk_add_f32 v[16:17], v[108:109], v[16:17]
	v_exp_f32_e32 v99, v233
	v_exp_f32_e32 v56, v236
	v_exp_f32_e32 v55, v235
	v_pk_add_f32 v[232:233], v[166:167], v[212:213] op_sel:[0,1] op_sel_hi:[1,1] neg_lo:[0,1] neg_hi:[0,1]
	v_pk_add_f32 v[16:17], v[58:59], v[16:17]
	v_exp_f32_e32 v57, v237
	v_exp_f32_e32 v40, v233
	v_pk_add_f32 v[16:17], v[62:63], v[16:17]
	v_exp_f32_e32 v41, v232
	v_pk_add_f32 v[232:233], v[168:169], v[212:213] op_sel:[0,1] op_sel_hi:[1,1] neg_lo:[0,1] neg_hi:[0,1]
	v_pk_add_f32 v[16:17], v[70:71], v[16:17]
	v_exp_f32_e32 v42, v232
	v_pk_add_f32 v[16:17], v[98:99], v[16:17]
	v_exp_f32_e32 v43, v233
	v_pk_add_f32 v[232:233], v[170:171], v[212:213] op_sel:[0,1] op_sel_hi:[1,1] neg_lo:[0,1] neg_hi:[0,1]
	v_pk_add_f32 v[0:1], v[56:57], v[16:17]
	v_exp_f32_e32 v44, v232
	v_pk_add_f32 v[0:1], v[60:61], v[0:1]
	v_exp_f32_e32 v45, v233
	v_pk_add_f32 v[232:233], v[172:173], v[212:213] op_sel:[0,1] op_sel_hi:[1,1] neg_lo:[0,1] neg_hi:[0,1]
	v_pk_add_f32 v[0:1], v[66:67], v[0:1]
	v_exp_f32_e32 v46, v232
	v_pk_add_f32 v[0:1], v[74:75], v[0:1]
	v_exp_f32_e32 v47, v233
	v_pk_add_f32 v[232:233], v[174:175], v[212:213] op_sel:[0,1] op_sel_hi:[1,1] neg_lo:[0,1] neg_hi:[0,1]
	v_pk_add_f32 v[0:1], v[48:49], v[0:1]
	v_exp_f32_e32 v32, v232
	v_pk_add_f32 v[0:1], v[50:51], v[0:1]
	v_exp_f32_e32 v33, v233
	v_pk_add_f32 v[232:233], v[176:177], v[212:213] op_sel:[0,1] op_sel_hi:[1,1] neg_lo:[0,1] neg_hi:[0,1]
	v_pk_add_f32 v[0:1], v[52:53], v[0:1]
	v_exp_f32_e32 v34, v232
	v_pk_add_f32 v[0:1], v[54:55], v[0:1]
	v_exp_f32_e32 v35, v233
	v_pk_add_f32 v[232:233], v[178:179], v[212:213] op_sel:[0,1] op_sel_hi:[1,1] neg_lo:[0,1] neg_hi:[0,1]
	v_pk_add_f32 v[0:1], v[40:41], v[0:1]
	v_exp_f32_e32 v36, v232
	v_pk_add_f32 v[0:1], v[42:43], v[0:1]
	v_exp_f32_e32 v37, v233
	v_pk_add_f32 v[232:233], v[180:181], v[212:213] op_sel:[0,1] op_sel_hi:[1,1] neg_lo:[0,1] neg_hi:[0,1]
	v_pk_add_f32 v[0:1], v[44:45], v[0:1]
	v_exp_f32_e32 v38, v232
	v_pk_add_f32 v[0:1], v[46:47], v[0:1]
	v_exp_f32_e32 v39, v233
	v_pk_add_f32 v[0:1], v[32:33], v[0:1]
	v_cvt_pk_bf16_f32 v16, v110, v111
	v_cvt_pk_bf16_f32 v17, v154, v155
	v_add_u32_e32 v154, 0x9000, v207
	v_pk_add_f32 v[0:1], v[34:35], v[0:1]
	v_cvt_pk_bf16_f32 v18, v160, v161
	v_cvt_pk_bf16_f32 v19, v164, v165
	v_add_u32_e32 v160, 0xd000, v207
	v_pk_add_f32 v[0:1], v[36:37], v[0:1]
	ds_read2_b64 v[20:23], v160 offset0:32 offset1:34
	v_pk_add_f32 v[0:1], v[38:39], v[0:1]
	s_nop 0
	v_add_f32_e32 v0, v0, v1
	ds_bpermute_b32 v1, v188, v0
	s_waitcnt lgkmcnt(0)
	v_add_f32_e32 v0, v0, v1
	v_sub_f32_e32 v1, v96, v213
	v_exp_f32_e32 v1, v1
	s_nop 0
	v_add_f32_e32 v96, v1, v0
	ds_read2_b64 v[0:3], v154 offset1:2
	v_cvt_pk_bf16_f32 v110, v102, v103
	v_cvt_pk_bf16_f32 v111, v112, v113
	v_cvt_pk_bf16_f32 v112, v156, v157
	v_cvt_pk_bf16_f32 v113, v162, v163
	ds_read2_b64 v[154:157], v154 offset0:4 offset1:6
	s_waitcnt lgkmcnt(1)
	v_mfma_f32_32x32x16_bf16 v[0:15], v[0:3], v[16:19], 0
	s_waitcnt lgkmcnt(0)
	v_mfma_f32_32x32x16_bf16 v[0:15], v[154:157], v[110:113], v[0:15]
	ds_read2_b64 v[154:157], v160 offset0:36 offset1:38
	v_mfma_f32_32x32x16_bf16 v[16:31], v[20:23], v[16:19], 0
	s_waitcnt lgkmcnt(0)
	v_mfma_f32_32x32x16_bf16 v[16:31], v[154:157], v[110:113], v[16:31]
	v_cvt_pk_bf16_f32 v110, v78, v79
	v_add_u32_e32 v78, 0x9000, v208
	v_cvt_pk_bf16_f32 v111, v106, v107
	v_cvt_pk_bf16_f32 v112, v118, v119
	v_cvt_pk_bf16_f32 v113, v158, v159
	ds_read2_b64 v[154:157], v78 offset1:2
	v_add_u32_e32 v106, 0xd000, v208
	s_waitcnt lgkmcnt(0)
	v_mfma_f32_32x32x16_bf16 v[0:15], v[154:157], v[110:113], v[0:15]
	ds_read2_b64 v[154:157], v106 offset0:32 offset1:34
	v_cvt_pk_bf16_f32 v102, v68, v69
	v_cvt_pk_bf16_f32 v103, v76, v77
	v_cvt_pk_bf16_f32 v104, v104, v105
	v_cvt_pk_bf16_f32 v105, v114, v115
	ds_read2_b64 v[76:79], v78 offset0:4 offset1:6
	s_waitcnt lgkmcnt(0)
	v_mfma_f32_32x32x16_bf16 v[0:15], v[76:79], v[102:105], v[0:15]
	ds_read2_b64 v[76:79], v106 offset0:36 offset1:38
	v_mfma_f32_32x32x16_bf16 v[16:31], v[154:157], v[110:113], v[16:31]
	s_waitcnt lgkmcnt(0)
	v_mfma_f32_32x32x16_bf16 v[16:31], v[76:79], v[102:105], v[16:31]
	v_cvt_pk_bf16_f32 v76, v64, v65
	v_add_u32_e32 v64, 0x9000, v209
	v_cvt_pk_bf16_f32 v77, v72, v73
	v_cvt_pk_bf16_f32 v78, v100, v101
	v_cvt_pk_bf16_f32 v79, v108, v109
	ds_read2_b64 v[100:103], v64 offset1:2
	v_add_u32_e32 v72, 0xd000, v209
	s_waitcnt lgkmcnt(0)
	v_mfma_f32_32x32x16_bf16 v[0:15], v[100:103], v[76:79], v[0:15]
	ds_read2_b64 v[100:103], v72 offset0:32 offset1:34
	v_cvt_pk_bf16_f32 v68, v58, v59
	v_cvt_pk_bf16_f32 v69, v62, v63
	v_cvt_pk_bf16_f32 v70, v70, v71
	v_cvt_pk_bf16_f32 v71, v98, v99
	ds_read2_b64 v[62:65], v64 offset0:4 offset1:6
	s_waitcnt lgkmcnt(0)
	v_mfma_f32_32x32x16_bf16 v[0:15], v[62:65], v[68:71], v[0:15]
	ds_read2_b64 v[62:65], v72 offset0:36 offset1:38
	v_cvt_pk_bf16_f32 v56, v56, v57
	v_cvt_pk_bf16_f32 v57, v60, v61
	v_cvt_pk_bf16_f32 v58, v66, v67
	v_cvt_pk_bf16_f32 v59, v74, v75
	v_mfma_f32_32x32x16_bf16 v[16:31], v[100:103], v[76:79], v[16:31]
	s_waitcnt lgkmcnt(0)
	v_mfma_f32_32x32x16_bf16 v[16:31], v[62:65], v[68:71], v[16:31]
	v_add_u32_e32 v64, 0x9000, v210
	ds_read2_b64 v[60:63], v64 offset1:2
	v_add_u32_e32 v65, 0xd000, v210
	s_waitcnt lgkmcnt(0)
	v_mfma_f32_32x32x16_bf16 v[0:15], v[60:63], v[56:59], v[0:15]
	ds_read2_b64 v[60:63], v65 offset0:32 offset1:34
	v_cvt_pk_bf16_f32 v48, v48, v49
	v_cvt_pk_bf16_f32 v49, v50, v51
	v_cvt_pk_bf16_f32 v50, v52, v53
	v_cvt_pk_bf16_f32 v51, v54, v55
	ds_read2_b64 v[52:55], v64 offset0:4 offset1:6
	s_waitcnt lgkmcnt(0)
	v_mfma_f32_32x32x16_bf16 v[0:15], v[52:55], v[48:51], v[0:15]
	ds_read2_b64 v[52:55], v65 offset0:36 offset1:38
	v_cvt_pk_bf16_f32 v40, v40, v41
	v_cvt_pk_bf16_f32 v41, v42, v43
	v_cvt_pk_bf16_f32 v42, v44, v45
	v_cvt_pk_bf16_f32 v43, v46, v47
	v_mfma_f32_32x32x16_bf16 v[16:31], v[60:63], v[56:59], v[16:31]
	s_waitcnt lgkmcnt(0)
	v_mfma_f32_32x32x16_bf16 v[16:31], v[52:55], v[48:51], v[16:31]
	v_add_u32_e32 v48, 0x9000, v211
	ds_read2_b64 v[44:47], v48 offset1:2
	v_add_u32_e32 v49, 0xd000, v211
	s_waitcnt lgkmcnt(0)
	v_mfma_f32_32x32x16_bf16 v[0:15], v[44:47], v[40:43], v[0:15]
	ds_read2_b64 v[44:47], v49 offset0:32 offset1:34
	v_cvt_pk_bf16_f32 v32, v32, v33
	v_cvt_pk_bf16_f32 v33, v34, v35
	v_cvt_pk_bf16_f32 v34, v36, v37
	v_cvt_pk_bf16_f32 v35, v38, v39
	ds_read2_b64 v[36:39], v48 offset0:4 offset1:6
	s_waitcnt lgkmcnt(0)
	v_mfma_f32_32x32x16_bf16 v[0:15], v[36:39], v[32:35], v[0:15]
	ds_read2_b64 v[36:39], v49 offset0:36 offset1:38
	v_mfma_f32_32x32x16_bf16 v[16:31], v[44:47], v[40:43], v[16:31]
	s_waitcnt lgkmcnt(0)
	v_mfma_f32_32x32x16_bf16 v[16:31], v[36:39], v[32:35], v[16:31]
	v_div_scale_f32 v32, s[68:69], v96, v96, 1.0
	v_rcp_f32_e32 v33, v32
	s_nop 0
	v_fma_f32 v34, -v32, v33, 1.0
	v_fmac_f32_e32 v33, v34, v33
	v_div_scale_f32 v34, vcc, 1.0, v96, 1.0
	v_mul_f32_e32 v35, v34, v33
	v_fma_f32 v36, -v32, v35, v34
	v_fmac_f32_e32 v35, v36, v33
	v_fma_f32 v32, -v32, v35, v34
	v_div_fmas_f32 v32, v32, v33, v35
	v_div_fixup_f32 v34, v32, v96, 1.0
	v_pk_mul_f32 v[0:1], v[0:1], v[34:35] op_sel_hi:[1,0]
	v_cvt_pk_bf16_f32 v0, v0, v1
	v_pk_mul_f32 v[2:3], v[2:3], v[34:35] op_sel_hi:[1,0]
	v_mad_i64_i32 v[32:33], s[68:69], v153, s65, v[116:117]
	v_and_b32_e32 v36, 63, v251
	v_and_b32_e32 v35, 31, v251
	v_lshrrev_b32_e32 v37, 5, v36
	v_lshlrev_b32_e32 v37, 3, v37
	s_movk_i32 s58, 0x90
	v_mad_u32_u24 v35, v35, s58, v37
	s_movk_i32 s59, 0x1200
	v_mad_u32_u24 v35, v254, s59, v35
	v_add_u32_e32 v35, 0x12000, v35
	v_lshrrev_b32_e32 v37, 3, v36
	v_and_b32_e32 v40, 7, v36
	v_lshlrev_b32_e32 v40, 4, v40
	v_mad_u32_u24 v36, v37, s58, v40
	v_mad_u32_u24 v36, v254, s59, v36
	v_add_u32_e32 v36, 0x12000, v36
	s_movk_i32 s58, 0xc00
	v_mad_u32_u24 v37, v37, s58, v40
	v_readfirstlane_b32 s56, v32
	v_readfirstlane_b32 s57, v33
	v_cvt_pk_bf16_f32 v1, v2, v3
	ds_write_b64 v35, v[0:1]
	v_pk_mul_f32 v[4:5], v[4:5], v[34:35] op_sel_hi:[1,0]
	v_cvt_pk_bf16_f32 v0, v4, v5
	v_pk_mul_f32 v[6:7], v[6:7], v[34:35] op_sel_hi:[1,0]
	v_cvt_pk_bf16_f32 v1, v6, v7
	ds_write_b64 v35, v[0:1] offset:16
	v_pk_mul_f32 v[8:9], v[8:9], v[34:35] op_sel_hi:[1,0]
	v_cvt_pk_bf16_f32 v0, v8, v9
	v_pk_mul_f32 v[10:11], v[10:11], v[34:35] op_sel_hi:[1,0]
	v_cvt_pk_bf16_f32 v1, v10, v11
	ds_write_b64 v35, v[0:1] offset:32
	v_pk_mul_f32 v[12:13], v[12:13], v[34:35] op_sel_hi:[1,0]
	v_cvt_pk_bf16_f32 v0, v12, v13
	v_pk_mul_f32 v[14:15], v[14:15], v[34:35] op_sel_hi:[1,0]
	v_cvt_pk_bf16_f32 v1, v14, v15
	ds_write_b64 v35, v[0:1] offset:48
	v_pk_mul_f32 v[16:17], v[16:17], v[34:35] op_sel_hi:[1,0]
	v_cvt_pk_bf16_f32 v0, v16, v17
	v_pk_mul_f32 v[18:19], v[18:19], v[34:35] op_sel_hi:[1,0]
	v_cvt_pk_bf16_f32 v1, v18, v19
	ds_write_b64 v35, v[0:1] offset:64
	v_pk_mul_f32 v[20:21], v[20:21], v[34:35] op_sel_hi:[1,0]
	v_cvt_pk_bf16_f32 v0, v20, v21
	v_pk_mul_f32 v[22:23], v[22:23], v[34:35] op_sel_hi:[1,0]
	v_cvt_pk_bf16_f32 v1, v22, v23
	ds_write_b64 v35, v[0:1] offset:80
	v_pk_mul_f32 v[24:25], v[24:25], v[34:35] op_sel_hi:[1,0]
	v_cvt_pk_bf16_f32 v0, v24, v25
	v_pk_mul_f32 v[26:27], v[26:27], v[34:35] op_sel_hi:[1,0]
	v_cvt_pk_bf16_f32 v1, v26, v27
	ds_write_b64 v35, v[0:1] offset:96
	v_pk_mul_f32 v[28:29], v[28:29], v[34:35] op_sel_hi:[1,0]
	v_cvt_pk_bf16_f32 v0, v28, v29
	v_pk_mul_f32 v[30:31], v[30:31], v[34:35] op_sel_hi:[1,0]
	s_andn2_b64 vcc, exec, s[76:77]
	v_cvt_pk_bf16_f32 v1, v30, v31
	ds_write_b64 v35, v[0:1] offset:112
	s_waitcnt lgkmcnt(0)
	ds_read_b128 v[0:3], v36
	ds_read_b128 v[4:7], v36 offset:1152
	ds_read_b128 v[8:11], v36 offset:2304
	ds_read_b128 v[12:15], v36 offset:3456
	s_waitcnt lgkmcnt(3)
	global_store_dwordx4 v37, v[0:3], s[56:57]
	s_add_u32 s56, s56, 0x6000
	s_addc_u32 s57, s57, 0
	s_waitcnt lgkmcnt(2)
	global_store_dwordx4 v37, v[4:7], s[56:57]
	s_add_u32 s56, s56, 0x6000
	s_addc_u32 s57, s57, 0
	s_waitcnt lgkmcnt(1)
	global_store_dwordx4 v37, v[8:11], s[56:57]
	s_add_u32 s56, s56, 0x6000
	s_addc_u32 s57, s57, 0
	s_waitcnt lgkmcnt(0)
	global_store_dwordx4 v37, v[12:15], s[56:57]
	s_nop 1
	s_setprio 0
	s_cbranch_vccz .Lattn_exit

.LBB0_357:
	s_mov_b32 s64, 0xff800000
	v_cndmask_b32_e64 v72, v48, v212, s[2:3]
	v_cndmask_b32_e64 v216, v72, v48, s[4:5]
	v_max3_f32 v48, v158, s64, v157
	v_max3_f32 v48, v48, v156, v155
	v_max3_f32 v48, v48, v154, v119
	v_max3_f32 v48, v48, v118, v99
	v_max3_f32 v48, v48, v71, v70
	v_max3_f32 v48, v48, v69, v68
	v_max3_f32 v48, v48, v67, v66
	v_max3_f32 v48, v48, v65, v64
	v_max3_f32 v48, v48, v32, v33
	v_max3_f32 v48, v48, v34, v35
	v_max3_f32 v48, v48, v36, v37
	v_max3_f32 v48, v48, v38, v39
	v_max3_f32 v48, v48, v40, v41
	v_max3_f32 v48, v48, v42, v43
	v_max3_f32 v48, v48, v44, v45
	v_max3_f32 v48, v48, v46, v47
	v_max3_f32 v48, v48, v16, v17
	v_max3_f32 v48, v48, v18, v19
	v_max3_f32 v48, v48, v20, v21
	v_max3_f32 v48, v48, v22, v23
	v_max3_f32 v48, v48, v24, v25
	v_max3_f32 v48, v48, v26, v27
	v_max3_f32 v48, v48, v28, v29
	v_max3_f32 v48, v48, v30, v31
	v_max3_f32 v48, v48, v0, v1
	v_max3_f32 v48, v48, v2, v3
	v_max3_f32 v48, v48, v4, v5
	v_max3_f32 v48, v48, v6, v7
	v_max3_f32 v48, v48, v8, v9
	v_max3_f32 v48, v48, v10, v11
	v_max3_f32 v48, v48, v12, v13
	v_cndmask_b32_e64 v215, v212, v49, s[4:5]
	v_max3_f32 v48, v48, v14, v15
	v_cndmask_b32_e64 v217, v50, v212, s[6:7]
	v_cndmask_b32_e64 v218, v51, v212, s[8:9]
	v_max3_f32 v48, v48, v216, v215
	v_cndmask_b32_e64 v219, v52, v212, s[10:11]
	v_cndmask_b32_e64 v220, v53, v212, s[12:13]
	v_max3_f32 v48, v48, v217, v218
	v_cndmask_b32_e64 v221, v54, v212, s[14:15]
	v_cndmask_b32_e64 v222, v55, v212, s[16:17]
	v_max3_f32 v48, v48, v219, v220
	v_cndmask_b32_e64 v223, v56, v212, s[18:19]
	v_cndmask_b32_e64 v224, v57, v212, s[20:21]
	v_max3_f32 v48, v48, v221, v222
	v_cndmask_b32_e64 v225, v58, v212, s[22:23]
	v_cndmask_b32_e64 v226, v59, v212, s[24:25]
	v_max3_f32 v48, v48, v223, v224
	v_cndmask_b32_e64 v227, v60, v212, s[26:27]
	v_cndmask_b32_e64 v228, v61, v212, s[28:29]
	v_max3_f32 v48, v48, v225, v226
	v_cndmask_b32_e64 v229, v62, v212, s[30:31]
	v_cndmask_b32_e64 v230, v63, v212, s[34:35]
	v_max3_f32 v48, v48, v227, v228
	v_max3_f32 v48, v48, v229, v230
	ds_bpermute_b32 v49, v188, v48
	v_mul_f32_e32 v96, 0x3fb8aa3b, v214
	v_or_b32_e32 v213, s89, v98
	s_mov_b32 s55, 0x3fb8aa3b
	s_lshl_b32 s94, s69, 1
	s_waitcnt lgkmcnt(0)
	v_max3_f32 v231, v48, v49, v96
	v_sub_f32_e32 v50, v156, v231
	v_exp_f32_e32 v170, v50
	v_sub_f32_e32 v50, v155, v231
	v_exp_f32_e32 v171, v50
	v_sub_f32_e32 v50, v154, v231
	v_exp_f32_e32 v176, v50
	v_sub_f32_e32 v50, v119, v231
	v_exp_f32_e32 v177, v50
	v_sub_f32_e32 v50, v118, v231
	v_sub_f32_e32 v48, v158, v231
	v_exp_f32_e32 v180, v50
	v_sub_f32_e32 v50, v99, v231
	v_exp_f32_e32 v162, v48
	v_sub_f32_e32 v48, v157, v231
	v_exp_f32_e32 v181, v50
	v_sub_f32_e32 v50, v71, v231
	v_exp_f32_e32 v163, v48
	v_exp_f32_e32 v154, v50
	v_sub_f32_e32 v50, v70, v231
	v_exp_f32_e32 v155, v50
	v_pk_add_f32 v[232:233], v[68:69], v[230:231] op_sel:[0,1] op_sel_hi:[1,1] neg_lo:[0,1] neg_hi:[0,1]
	v_pk_add_f32 v[234:235], v[34:35], v[230:231] op_sel:[0,1] op_sel_hi:[1,1] neg_lo:[0,1] neg_hi:[0,1]
	v_exp_f32_e32 v164, v233
	v_exp_f32_e32 v158, v234
	v_exp_f32_e32 v165, v232
	v_pk_add_f32 v[232:233], v[66:67], v[230:231] op_sel:[0,1] op_sel_hi:[1,1] neg_lo:[0,1] neg_hi:[0,1]
	v_exp_f32_e32 v159, v235
	v_pk_add_f32 v[234:235], v[36:37], v[230:231] op_sel:[0,1] op_sel_hi:[1,1] neg_lo:[0,1] neg_hi:[0,1]
	v_pk_add_f32 v[48:49], v[162:163], 0 op_sel_hi:[1,0]
	v_exp_f32_e32 v172, v233
	v_exp_f32_e32 v166, v234
	v_pk_add_f32 v[48:49], v[170:171], v[48:49]
	v_exp_f32_e32 v173, v232
	v_pk_add_f32 v[232:233], v[64:65], v[230:231] op_sel:[0,1] op_sel_hi:[1,1] neg_lo:[0,1] neg_hi:[0,1]
	v_exp_f32_e32 v167, v235
	v_pk_add_f32 v[234:235], v[38:39], v[230:231] op_sel:[0,1] op_sel_hi:[1,1] neg_lo:[0,1] neg_hi:[0,1]
	v_pk_add_f32 v[48:49], v[176:177], v[48:49]
	v_exp_f32_e32 v178, v233
	v_pk_add_f32 v[236:237], v[32:33], v[230:231] op_sel:[0,1] op_sel_hi:[1,1] neg_lo:[0,1] neg_hi:[0,1]
	v_exp_f32_e32 v174, v234
	v_pk_add_f32 v[48:49], v[180:181], v[48:49]
	v_exp_f32_e32 v179, v232
	v_exp_f32_e32 v78, v236
	v_exp_f32_e32 v175, v235
	v_pk_add_f32 v[232:233], v[40:41], v[230:231] op_sel:[0,1] op_sel_hi:[1,1] neg_lo:[0,1] neg_hi:[0,1]
	v_pk_add_f32 v[48:49], v[154:155], v[48:49]
	v_exp_f32_e32 v79, v237
	v_exp_f32_e32 v70, v232
	v_pk_add_f32 v[48:49], v[164:165], v[48:49]
	v_exp_f32_e32 v71, v233
	v_pk_add_f32 v[232:233], v[42:43], v[230:231] op_sel:[0,1] op_sel_hi:[1,1] neg_lo:[0,1] neg_hi:[0,1]
	v_pk_add_f32 v[234:235], v[18:19], v[230:231] op_sel:[0,1] op_sel_hi:[1,1] neg_lo:[0,1] neg_hi:[0,1]
	v_pk_add_f32 v[236:237], v[2:3], v[230:231] op_sel:[0,1] op_sel_hi:[1,1] neg_lo:[0,1] neg_hi:[0,1]
	v_pk_add_f32 v[48:49], v[172:173], v[48:49]
	v_exp_f32_e32 v76, v232
	v_exp_f32_e32 v74, v234
	v_exp_f32_e32 v60, v236
	v_pk_add_f32 v[48:49], v[178:179], v[48:49]
	v_exp_f32_e32 v77, v233
	v_pk_add_f32 v[232:233], v[44:45], v[230:231] op_sel:[0,1] op_sel_hi:[1,1] neg_lo:[0,1] neg_hi:[0,1]
	v_exp_f32_e32 v75, v235
	v_pk_add_f32 v[234:235], v[20:21], v[230:231] op_sel:[0,1] op_sel_hi:[1,1] neg_lo:[0,1] neg_hi:[0,1]
	v_exp_f32_e32 v61, v237
	v_pk_add_f32 v[236:237], v[4:5], v[230:231] op_sel:[0,1] op_sel_hi:[1,1] neg_lo:[0,1] neg_hi:[0,1]
	v_pk_add_f32 v[32:33], v[78:79], v[48:49]
	v_exp_f32_e32 v156, v232
	v_exp_f32_e32 v98, v234
	v_exp_f32_e32 v66, v236
	v_pk_add_f32 v[32:33], v[158:159], v[32:33]
	v_exp_f32_e32 v157, v233
	v_pk_add_f32 v[232:233], v[46:47], v[230:231] op_sel:[0,1] op_sel_hi:[1,1] neg_lo:[0,1] neg_hi:[0,1]
	v_exp_f32_e32 v99, v235
	v_pk_add_f32 v[234:235], v[22:23], v[230:231] op_sel:[0,1] op_sel_hi:[1,1] neg_lo:[0,1] neg_hi:[0,1]
	v_exp_f32_e32 v67, v237
	v_pk_add_f32 v[236:237], v[6:7], v[230:231] op_sel:[0,1] op_sel_hi:[1,1] neg_lo:[0,1] neg_hi:[0,1]
	v_pk_add_f32 v[32:33], v[166:167], v[32:33]
	v_exp_f32_e32 v168, v232
	v_pk_add_f32 v[238:239], v[16:17], v[230:231] op_sel:[0,1] op_sel_hi:[1,1] neg_lo:[0,1] neg_hi:[0,1]
	v_exp_f32_e32 v160, v234
	v_exp_f32_e32 v68, v236
	v_pk_add_f32 v[32:33], v[174:175], v[32:33]
	v_exp_f32_e32 v169, v233
	v_exp_f32_e32 v64, v238
	v_exp_f32_e32 v161, v235
	v_pk_add_f32 v[232:233], v[24:25], v[230:231] op_sel:[0,1] op_sel_hi:[1,1] neg_lo:[0,1] neg_hi:[0,1]
	v_exp_f32_e32 v69, v237
	v_pk_add_f32 v[234:235], v[8:9], v[230:231] op_sel:[0,1] op_sel_hi:[1,1] neg_lo:[0,1] neg_hi:[0,1]
	v_pk_add_f32 v[32:33], v[70:71], v[32:33]
	v_exp_f32_e32 v65, v239
	v_exp_f32_e32 v58, v232
	v_exp_f32_e32 v48, v234
	v_pk_add_f32 v[32:33], v[76:77], v[32:33]
	v_exp_f32_e32 v59, v233
	v_pk_add_f32 v[232:233], v[26:27], v[230:231] op_sel:[0,1] op_sel_hi:[1,1] neg_lo:[0,1] neg_hi:[0,1]
	v_exp_f32_e32 v49, v235
	v_pk_add_f32 v[234:235], v[10:11], v[230:231] op_sel:[0,1] op_sel_hi:[1,1] neg_lo:[0,1] neg_hi:[0,1]
	v_pk_add_f32 v[32:33], v[156:157], v[32:33]
	v_exp_f32_e32 v62, v232
	v_exp_f32_e32 v50, v234
	v_pk_add_f32 v[32:33], v[168:169], v[32:33]
	v_exp_f32_e32 v63, v233
	v_pk_add_f32 v[232:233], v[28:29], v[230:231] op_sel:[0,1] op_sel_hi:[1,1] neg_lo:[0,1] neg_hi:[0,1]
	v_exp_f32_e32 v51, v235
	v_pk_add_f32 v[234:235], v[12:13], v[230:231] op_sel:[0,1] op_sel_hi:[1,1] neg_lo:[0,1] neg_hi:[0,1]
	v_pk_add_f32 v[16:17], v[64:65], v[32:33]
	v_exp_f32_e32 v72, v232
	v_exp_f32_e32 v52, v234
	v_pk_add_f32 v[16:17], v[74:75], v[16:17]
	v_exp_f32_e32 v73, v233
	v_pk_add_f32 v[232:233], v[30:31], v[230:231] op_sel:[0,1] op_sel_hi:[1,1] neg_lo:[0,1] neg_hi:[0,1]
	v_exp_f32_e32 v53, v235
	v_pk_add_f32 v[234:235], v[14:15], v[230:231] op_sel:[0,1] op_sel_hi:[1,1] neg_lo:[0,1] neg_hi:[0,1]
	v_pk_add_f32 v[16:17], v[98:99], v[16:17]
	v_exp_f32_e32 v118, v232
	v_pk_add_f32 v[236:237], v[0:1], v[230:231] op_sel:[0,1] op_sel_hi:[1,1] neg_lo:[0,1] neg_hi:[0,1]
	v_exp_f32_e32 v54, v234
	v_pk_add_f32 v[16:17], v[160:161], v[16:17]
	v_exp_f32_e32 v119, v233
	v_exp_f32_e32 v56, v236
	v_exp_f32_e32 v55, v235
	v_pk_add_f32 v[232:233], v[216:217], v[230:231] op_sel:[0,1] op_sel_hi:[1,1] neg_lo:[0,1] neg_hi:[0,1]
	v_pk_add_f32 v[16:17], v[58:59], v[16:17]
	v_exp_f32_e32 v57, v237
	v_exp_f32_e32 v40, v232
	v_sub_f32_e32 v2, v215, v231
	v_pk_add_f32 v[16:17], v[62:63], v[16:17]
	v_exp_f32_e32 v41, v2
	v_pk_add_f32 v[16:17], v[72:73], v[16:17]
	v_exp_f32_e32 v42, v233
	v_pk_add_f32 v[232:233], v[218:219], v[230:231] op_sel:[0,1] op_sel_hi:[1,1] neg_lo:[0,1] neg_hi:[0,1]
	v_pk_add_f32 v[16:17], v[118:119], v[16:17]
	v_exp_f32_e32 v43, v232
	v_pk_add_f32 v[0:1], v[56:57], v[16:17]
	v_exp_f32_e32 v44, v233
	v_pk_add_f32 v[232:233], v[220:221], v[230:231] op_sel:[0,1] op_sel_hi:[1,1] neg_lo:[0,1] neg_hi:[0,1]
	v_pk_add_f32 v[0:1], v[60:61], v[0:1]
	v_exp_f32_e32 v45, v232
	v_pk_add_f32 v[0:1], v[66:67], v[0:1]
	v_exp_f32_e32 v46, v233
	v_pk_add_f32 v[232:233], v[222:223], v[230:231] op_sel:[0,1] op_sel_hi:[1,1] neg_lo:[0,1] neg_hi:[0,1]
	v_pk_add_f32 v[0:1], v[68:69], v[0:1]
	v_exp_f32_e32 v47, v232
	v_pk_add_f32 v[0:1], v[48:49], v[0:1]
	v_exp_f32_e32 v32, v233
	v_pk_add_f32 v[232:233], v[224:225], v[230:231] op_sel:[0,1] op_sel_hi:[1,1] neg_lo:[0,1] neg_hi:[0,1]
	v_pk_add_f32 v[0:1], v[50:51], v[0:1]
	v_exp_f32_e32 v33, v232
	v_pk_add_f32 v[0:1], v[52:53], v[0:1]
	v_exp_f32_e32 v34, v233
	v_pk_add_f32 v[232:233], v[226:227], v[230:231] op_sel:[0,1] op_sel_hi:[1,1] neg_lo:[0,1] neg_hi:[0,1]
	v_pk_add_f32 v[0:1], v[54:55], v[0:1]
	v_exp_f32_e32 v35, v232
	v_pk_add_f32 v[0:1], v[40:41], v[0:1]
	v_exp_f32_e32 v36, v233
	v_pk_add_f32 v[232:233], v[228:229], v[230:231] op_sel:[0,1] op_sel_hi:[1,1] neg_lo:[0,1] neg_hi:[0,1]
	v_pk_add_f32 v[0:1], v[42:43], v[0:1]
	v_exp_f32_e32 v37, v232
	v_pk_add_f32 v[0:1], v[44:45], v[0:1]
	v_exp_f32_e32 v38, v233
	v_sub_f32_e32 v2, v230, v231
	v_pk_add_f32 v[0:1], v[46:47], v[0:1]
	v_exp_f32_e32 v39, v2
	v_pk_add_f32 v[0:1], v[32:33], v[0:1]
	v_cvt_pk_bf16_f32 v16, v162, v163
	v_cvt_pk_bf16_f32 v17, v170, v171
	v_add_u32_e32 v170, 0x9000, v197
	v_pk_add_f32 v[0:1], v[34:35], v[0:1]
	v_cvt_pk_bf16_f32 v18, v176, v177
	v_cvt_pk_bf16_f32 v19, v180, v181
	v_add_u32_e32 v176, 0xd000, v197
	v_pk_add_f32 v[0:1], v[36:37], v[0:1]
	ds_read2_b64 v[20:23], v176 offset0:32 offset1:34
	v_pk_add_f32 v[0:1], v[38:39], v[0:1]
	v_lshl_add_u64 v[116:117], v[146:147], 0, s[94:95]
	v_add_f32_e32 v0, v0, v1
	ds_bpermute_b32 v1, v188, v0
	s_mov_b32 s97, s0
	v_readlane_b32 s0, v255, 15
	s_waitcnt lgkmcnt(0)
	v_add_f32_e32 v0, v0, v1
	v_fma_f32 v1, v214, s55, -v231
	v_exp_f32_e32 v1, v1
	s_nop 0
	v_add_f32_e32 v214, v1, v0
	ds_read2_b64 v[0:3], v170 offset1:2
	v_cvt_pk_bf16_f32 v162, v154, v155
	v_cvt_pk_bf16_f32 v163, v164, v165
	v_cvt_pk_bf16_f32 v164, v172, v173
	v_cvt_pk_bf16_f32 v165, v178, v179
	ds_read2_b64 v[170:173], v170 offset0:4 offset1:6
	s_waitcnt lgkmcnt(1)
	v_mfma_f32_32x32x16_bf16 v[0:15], v[0:3], v[16:19], 0
	s_waitcnt lgkmcnt(0)
	v_mfma_f32_32x32x16_bf16 v[0:15], v[170:173], v[162:165], v[0:15]
	ds_read2_b64 v[170:173], v176 offset0:36 offset1:38
	v_mfma_f32_32x32x16_bf16 v[16:31], v[20:23], v[16:19], 0
	s_waitcnt lgkmcnt(0)
	v_mfma_f32_32x32x16_bf16 v[16:31], v[170:173], v[162:165], v[16:31]
	v_cvt_pk_bf16_f32 v162, v78, v79
	v_add_u32_e32 v78, 0x9000, v198
	v_cvt_pk_bf16_f32 v163, v158, v159
	v_cvt_pk_bf16_f32 v164, v166, v167
	v_cvt_pk_bf16_f32 v165, v174, v175
	ds_read2_b64 v[170:173], v78 offset1:2
	v_add_u32_e32 v158, 0xd000, v198
	s_waitcnt lgkmcnt(0)
	v_mfma_f32_32x32x16_bf16 v[0:15], v[170:173], v[162:165], v[0:15]
	ds_read2_b64 v[170:173], v158 offset0:32 offset1:34
	v_cvt_pk_bf16_f32 v154, v70, v71
	v_cvt_pk_bf16_f32 v155, v76, v77
	v_cvt_pk_bf16_f32 v156, v156, v157
	v_cvt_pk_bf16_f32 v157, v168, v169
	ds_read2_b64 v[76:79], v78 offset0:4 offset1:6
	s_waitcnt lgkmcnt(0)
	v_mfma_f32_32x32x16_bf16 v[0:15], v[76:79], v[154:157], v[0:15]
	ds_read2_b64 v[76:79], v158 offset0:36 offset1:38
	v_mfma_f32_32x32x16_bf16 v[16:31], v[170:173], v[162:165], v[16:31]
	s_waitcnt lgkmcnt(0)
	v_mfma_f32_32x32x16_bf16 v[16:31], v[76:79], v[154:157], v[16:31]
	v_cvt_pk_bf16_f32 v76, v64, v65
	v_add_u32_e32 v64, 0x9000, v199
	v_cvt_pk_bf16_f32 v77, v74, v75
	v_cvt_pk_bf16_f32 v78, v98, v99
	v_cvt_pk_bf16_f32 v79, v160, v161
	ds_read2_b64 v[154:157], v64 offset1:2
	v_add_u32_e32 v74, 0xd000, v199
	s_waitcnt lgkmcnt(0)
	v_mfma_f32_32x32x16_bf16 v[0:15], v[154:157], v[76:79], v[0:15]
	ds_read2_b64 v[154:157], v74 offset0:32 offset1:34
	v_cvt_pk_bf16_f32 v70, v58, v59
	v_cvt_pk_bf16_f32 v71, v62, v63
	v_cvt_pk_bf16_f32 v72, v72, v73
	v_cvt_pk_bf16_f32 v73, v118, v119
	ds_read2_b64 v[62:65], v64 offset0:4 offset1:6
	v_or_b32_e32 v118, s0, v153
	s_waitcnt lgkmcnt(0)
	v_mfma_f32_32x32x16_bf16 v[0:15], v[62:65], v[70:73], v[0:15]
	ds_read2_b64 v[62:65], v74 offset0:36 offset1:38
	v_cvt_pk_bf16_f32 v56, v56, v57
	v_cvt_pk_bf16_f32 v57, v60, v61
	v_cvt_pk_bf16_f32 v58, v66, v67
	v_cvt_pk_bf16_f32 v59, v68, v69
	v_and_b32_e32 v67, 0xffff0000, v103
	v_and_b32_e32 v66, 0xffff0000, v107
	v_mfma_f32_32x32x16_bf16 v[16:31], v[154:157], v[76:79], v[16:31]
	v_lshlrev_b32_e32 v155, 16, v100
	v_lshlrev_b32_e32 v154, 16, v104
	v_and_b32_e32 v79, 0xffff0000, v102
	v_mul_f32_e64 v156, v154, v154
	v_mul_f32_e64 v157, v155, v155
	v_and_b32_e32 v78, 0xffff0000, v106
	v_pk_mul_f32 v[98:99], v[78:79], v[78:79]
	v_pk_mul_f32 v[68:69], v[66:67], v[66:67]
	s_waitcnt lgkmcnt(0)
	v_mfma_f32_32x32x16_bf16 v[16:31], v[62:65], v[70:73], v[16:31]
	v_add_u32_e32 v64, 0x9000, v200
	ds_read2_b64 v[60:63], v64 offset1:2
	v_add_u32_e32 v65, 0xd000, v200
	v_lshlrev_b32_e32 v71, 16, v102
	v_lshlrev_b32_e32 v102, 16, v105
	v_lshlrev_b32_e32 v70, 16, v106
	v_pk_mul_f32 v[72:73], v[70:71], v[70:71]
	s_waitcnt lgkmcnt(0)
	v_mfma_f32_32x32x16_bf16 v[0:15], v[60:63], v[56:59], v[0:15]
	ds_read2_b64 v[60:63], v65 offset0:32 offset1:34
	v_cvt_pk_bf16_f32 v48, v48, v49
	v_cvt_pk_bf16_f32 v49, v50, v51
	v_cvt_pk_bf16_f32 v50, v52, v53
	v_cvt_pk_bf16_f32 v51, v54, v55
	ds_read2_b64 v[52:55], v64 offset0:4 offset1:6
	s_waitcnt lgkmcnt(0)
	v_mfma_f32_32x32x16_bf16 v[0:15], v[52:55], v[48:51], v[0:15]
	ds_read2_b64 v[52:55], v65 offset0:36 offset1:38
	v_cvt_pk_bf16_f32 v40, v40, v41
	v_cvt_pk_bf16_f32 v41, v42, v43
	v_cvt_pk_bf16_f32 v42, v44, v45
	v_cvt_pk_bf16_f32 v43, v46, v47
	v_mfma_f32_32x32x16_bf16 v[16:31], v[60:63], v[56:59], v[16:31]
	v_lshlrev_b32_e32 v59, 16, v103
	v_lshlrev_b32_e32 v103, 16, v101
	v_lshlrev_b32_e32 v58, 16, v107
	v_mul_f32_e64 v106, v102, v102
	v_mul_f32_e64 v107, v103, v103
	v_pk_mul_f32 v[60:61], v[58:59], v[58:59]
	s_waitcnt lgkmcnt(0)
	v_mfma_f32_32x32x16_bf16 v[16:31], v[52:55], v[48:51], v[16:31]
	v_add_u32_e32 v48, 0x9000, v201
	ds_read2_b64 v[44:47], v48 offset1:2
	v_add_u32_e32 v49, 0xd000, v201
	s_waitcnt lgkmcnt(0)
	v_mfma_f32_32x32x16_bf16 v[0:15], v[44:47], v[40:43], v[0:15]
	ds_read2_b64 v[44:47], v49 offset0:32 offset1:34
	v_cvt_pk_bf16_f32 v32, v32, v33
	v_cvt_pk_bf16_f32 v33, v34, v35
	v_cvt_pk_bf16_f32 v34, v36, v37
	v_cvt_pk_bf16_f32 v35, v38, v39
	ds_read2_b64 v[36:39], v48 offset0:4 offset1:6
	s_waitcnt lgkmcnt(0)
	v_mfma_f32_32x32x16_bf16 v[0:15], v[36:39], v[32:35], v[0:15]
	ds_read2_b64 v[36:39], v49 offset0:36 offset1:38
	v_mfma_f32_32x32x16_bf16 v[16:31], v[44:47], v[40:43], v[16:31]
	v_lshlrev_b32_e32 v42, 16, v112
	v_lshlrev_b32_e32 v43, 16, v108
	v_mul_f32_e64 v54, v42, v42
	v_mul_f32_e64 v55, v43, v43
	s_waitcnt lgkmcnt(0)
	v_mfma_f32_32x32x16_bf16 v[16:31], v[36:39], v[32:35], v[16:31]
	v_div_scale_f32 v32, s[68:69], v214, v214, 1.0
	v_rcp_f32_e32 v33, v32
	v_lshlrev_b32_e32 v38, 16, v113
	v_mov_b32_e32 v41, v38
	v_lshlrev_b32_e32 v39, 16, v109
	v_fma_f32 v34, -v32, v33, 1.0
	v_fmac_f32_e32 v33, v34, v33
	v_div_scale_f32 v34, vcc, 1.0, v214, 1.0
	v_mul_f32_e32 v35, v34, v33
	v_fma_f32 v36, -v32, v35, v34
	v_fmac_f32_e32 v35, v36, v33
	v_fma_f32 v32, -v32, v35, v34
	v_div_fmas_f32 v32, v32, v33, v35
	v_div_fixup_f32 v34, v32, v214, 1.0
	v_pk_mul_f32 v[0:1], v[0:1], v[34:35] op_sel_hi:[1,0]
	v_cvt_pk_bf16_f32 v0, v0, v1
	v_pk_mul_f32 v[2:3], v[2:3], v[34:35] op_sel_hi:[1,0]
	v_mad_i64_i32 v[32:33], s[68:69], v213, s65, v[116:117]
	v_and_b32_e32 v36, 63, v251
	v_and_b32_e32 v35, 31, v251
	v_lshrrev_b32_e32 v37, 5, v36
	v_lshlrev_b32_e32 v37, 3, v37
	s_movk_i32 s58, 0x90
	v_mad_u32_u24 v35, v35, s58, v37
	s_movk_i32 s59, 0x1200
	v_mad_u32_u24 v35, v254, s59, v35
	v_add_u32_e32 v35, 0x12000, v35
	v_lshrrev_b32_e32 v37, 3, v36
	v_and_b32_e32 v40, 7, v36
	v_lshlrev_b32_e32 v40, 4, v40
	v_mad_u32_u24 v36, v37, s58, v40
	v_mad_u32_u24 v36, v254, s59, v36
	v_add_u32_e32 v36, 0x12000, v36
	s_movk_i32 s58, 0xc00
	v_mad_u32_u24 v37, v37, s58, v40
	v_readfirstlane_b32 s56, v32
	v_readfirstlane_b32 s57, v33
	v_cvt_pk_bf16_f32 v1, v2, v3
	ds_write_b64 v35, v[0:1]
	v_pk_mul_f32 v[4:5], v[4:5], v[34:35] op_sel_hi:[1,0]
	v_cvt_pk_bf16_f32 v0, v4, v5
	v_pk_mul_f32 v[6:7], v[6:7], v[34:35] op_sel_hi:[1,0]
	v_cvt_pk_bf16_f32 v1, v6, v7
	ds_write_b64 v35, v[0:1] offset:16
	v_pk_mul_f32 v[8:9], v[8:9], v[34:35] op_sel_hi:[1,0]
	v_cvt_pk_bf16_f32 v0, v8, v9
	v_pk_mul_f32 v[10:11], v[10:11], v[34:35] op_sel_hi:[1,0]
	v_cvt_pk_bf16_f32 v1, v10, v11
	ds_write_b64 v35, v[0:1] offset:32
	v_pk_mul_f32 v[12:13], v[12:13], v[34:35] op_sel_hi:[1,0]
	v_cvt_pk_bf16_f32 v0, v12, v13
	v_pk_mul_f32 v[14:15], v[14:15], v[34:35] op_sel_hi:[1,0]
	v_cvt_pk_bf16_f32 v1, v14, v15
	ds_write_b64 v35, v[0:1] offset:48
	v_pk_mul_f32 v[16:17], v[16:17], v[34:35] op_sel_hi:[1,0]
	v_cvt_pk_bf16_f32 v0, v16, v17
	v_pk_mul_f32 v[18:19], v[18:19], v[34:35] op_sel_hi:[1,0]
	v_cvt_pk_bf16_f32 v1, v18, v19
	ds_write_b64 v35, v[0:1] offset:64
	v_pk_mul_f32 v[20:21], v[20:21], v[34:35] op_sel_hi:[1,0]
	v_cvt_pk_bf16_f32 v0, v20, v21
	v_pk_mul_f32 v[22:23], v[22:23], v[34:35] op_sel_hi:[1,0]
	v_cvt_pk_bf16_f32 v1, v22, v23
	ds_write_b64 v35, v[0:1] offset:80
	v_pk_mul_f32 v[24:25], v[24:25], v[34:35] op_sel_hi:[1,0]
	v_cvt_pk_bf16_f32 v0, v24, v25
	v_pk_mul_f32 v[26:27], v[26:27], v[34:35] op_sel_hi:[1,0]
	v_cvt_pk_bf16_f32 v1, v26, v27
	ds_write_b64 v35, v[0:1] offset:96
	v_pk_mul_f32 v[28:29], v[28:29], v[34:35] op_sel_hi:[1,0]
	v_cvt_pk_bf16_f32 v0, v28, v29
	v_pk_mul_f32 v[30:31], v[30:31], v[34:35] op_sel_hi:[1,0]
	v_cvt_pk_bf16_f32 v1, v30, v31
	ds_write_b64 v35, v[0:1] offset:112
	s_waitcnt lgkmcnt(0)
	ds_read_b128 v[0:3], v36
	ds_read_b128 v[4:7], v36 offset:1152
	ds_read_b128 v[8:11], v36 offset:2304
	ds_read_b128 v[12:15], v36 offset:3456
	s_waitcnt lgkmcnt(3)
	global_store_dwordx4 v37, v[0:3], s[56:57]
	s_add_u32 s56, s56, 0x6000
	s_addc_u32 s57, s57, 0
	s_waitcnt lgkmcnt(2)
	global_store_dwordx4 v37, v[4:7], s[56:57]
	s_add_u32 s56, s56, 0x6000
	s_addc_u32 s57, s57, 0
	s_waitcnt lgkmcnt(1)
	global_store_dwordx4 v37, v[8:11], s[56:57]
	s_add_u32 s56, s56, 0x6000
	s_addc_u32 s57, s57, 0
	s_waitcnt lgkmcnt(0)
	global_store_dwordx4 v37, v[12:15], s[56:57]
	s_nop 1
	s_and_b64 vcc, exec, s[76:77]
	s_cbranch_vccnz .Lvpf_skip
	s_lshl_b32 s58, s33, 5
	s_and_b32 s58, s58, 0x780
	s_addk_i32 s58, 0xff80
	v_add_u32_e32 v16, s58, v183
	v_cmp_lt_i32_e32 vcc, -1, v16
	v_mov_b32_e32 v122, 0
	v_mov_b32_e32 v123, 0
	v_mov_b32_e32 v124, 0
	v_mov_b32_e32 v125, 0
	v_mov_b32_e32 v128, 0
	v_mov_b32_e32 v129, 0
	v_mov_b32_e32 v130, 0
	v_mov_b32_e32 v131, 0
	v_mov_b32_e32 v132, 0
	v_mov_b32_e32 v133, 0
	v_mov_b32_e32 v134, 0
	v_mov_b32_e32 v135, 0
	v_mov_b32_e32 v136, 0
	v_mov_b32_e32 v137, 0
	v_mov_b32_e32 v138, 0
	v_mov_b32_e32 v139, 0
	s_and_saveexec_b64 s[80:81], vcc
	s_cbranch_execz .Lvpf_join
	v_readlane_b32 vcc_lo, v255, 6
	v_readlane_b32 vcc_hi, v255, 7
	s_ashr_i32 s59, s33, 6
	v_add_u32_e32 v18, s58, v250
	v_lshl_add_u32 v18, s59, 11, v18
	s_and_b32 s58, s33, 3
	s_lshl_b32 s58, s58, 7
	s_mov_b32 s59, 0
	v_mov_b64_e32 v[16:17], vcc
	v_mad_i64_i32 v[16:17], vcc, v18, s65, v[16:17]
	v_lshl_add_u64 v[16:17], v[16:17], 0, s[58:59]
	v_lshl_add_u64 v[16:17], v[16:17], 0, v[248:249]
	s_movk_i32 s58, 0x6000
	global_load_dwordx4 v[122:125], v[16:17], off offset:2560
	v_lshl_add_u64 v[16:17], v[16:17], 0, s[58:59]
	global_load_dwordx4 v[128:131], v[16:17], off offset:2560
	v_lshl_add_u64 v[16:17], v[16:17], 0, s[58:59]
	global_load_dwordx4 v[132:135], v[16:17], off offset:2560
	v_lshl_add_u64 v[16:17], v[16:17], 0, s[58:59]
	global_load_dwordx4 v[136:139], v[16:17], off offset:2560
